# spread mLSTM scan units one per CU (wave 0 of every WG + wave 4 of 32 WGs) instead of first-come
# speedup vs baseline: 1.0549x; 1.0549x over previous
.LBB0_316:
	s_or_b64 exec, exec, s[4:5]
	s_add_u32 s1, s68, 0x162e0800
	s_addc_u32 s26, s69, 0
	s_add_u32 s46, s68, 0x1d00800
	v_mov_b32_e32 v183, v254
	s_addc_u32 s47, s69, 0
	v_mbcnt_lo_u32_b32 v0, -1, 0
	s_barrier
	s_add_u32 s27, s68, 0x1f2e0800
	v_and_b32_e32 v182, 63, v183
	v_mbcnt_hi_u32_b32 v181, -1, v0
	v_bfrev_b32_e32 v0, 0.5
	v_readfirstlane_b32 s0, v183
	s_mov_b32 s13, 0
	v_cmp_eq_u32_e64 s[4:5], 0, v182
	s_addc_u32 s52, s69, 0
	v_mov_b32_e32 v157, 0
	s_mov_b32 s53, 0x1e2e0000
	s_mov_b32 s54, 0x1e2e1000
	s_mov_b32 s55, 0x1e2e2000
	s_mov_b32 s70, 0x2280000
	s_mov_b32 s71, 0x2281000
	s_mov_b32 s72, 0x2282000
	s_mov_b32 s73, 0x2283000
	s_mov_b32 s74, 0x2284000
	s_mov_b32 s75, 0x5040100
	s_mov_b64 s[14:15], 0x100
	s_mov_b64 s[16:17], 0x4000
	s_mov_b64 s[18:19], 0x2000
	v_and_b32_e32 v184, 64, v181
	v_lshl_or_b32 v185, v181, 2, v0
	v_mov_b32_e32 v186, 0x3f803f80
	v_mov_b32_e32 v187, 0x80
	s_lshr_b32 s98, s0, 6
	s_cmp_eq_u32 s98, 0
	s_cbranch_scc1 .LBB0_319
	s_cmp_lg_u32 s98, 4
	s_cbranch_scc1 .LBB0_366
	s_cmp_gt_u32 s2, 31
	s_cbranch_scc1 .LBB0_366
	s_branch .LBB0_319

	.amdhsa_kernel _Z10fwd_kernel7KParams
		.amdhsa_group_segment_fixed_size 0
		.amdhsa_private_segment_fixed_size 0
		.amdhsa_kernarg_size 472
		.amdhsa_user_sgpr_count 2
		.amdhsa_user_sgpr_dispatch_ptr 0
		.amdhsa_user_sgpr_queue_ptr 0
		.amdhsa_user_sgpr_kernarg_segment_ptr 1
		.amdhsa_user_sgpr_dispatch_id 0
		.amdhsa_user_sgpr_kernarg_preload_length 0
		.amdhsa_user_sgpr_kernarg_preload_offset 0
		.amdhsa_user_sgpr_private_segment_size 0
		.amdhsa_uses_dynamic_stack 0
		.amdhsa_enable_private_segment 0
		.amdhsa_system_sgpr_workgroup_id_x 1
		.amdhsa_system_sgpr_workgroup_id_y 0
		.amdhsa_system_sgpr_workgroup_id_z 0
		.amdhsa_system_sgpr_workgroup_info 0
		.amdhsa_system_vgpr_workitem_id 2
		.amdhsa_next_free_vgpr 256
		.amdhsa_next_free_sgpr 99
		.amdhsa_accum_offset 256
		.amdhsa_reserve_vcc 1
		.amdhsa_float_round_mode_32 0
		.amdhsa_float_round_mode_16_64 0
		.amdhsa_float_denorm_mode_32 3
		.amdhsa_float_denorm_mode_16_64 3
		.amdhsa_dx10_clamp 1
		.amdhsa_ieee_mode 1
		.amdhsa_fp16_overflow 0
		.amdhsa_tg_split 0
		.amdhsa_exception_fp_ieee_invalid_op 0
		.amdhsa_exception_fp_denorm_src 0
		.amdhsa_exception_fp_ieee_div_zero 0
		.amdhsa_exception_fp_ieee_overflow 0
		.amdhsa_exception_fp_ieee_underflow 0
		.amdhsa_exception_fp_ieee_inexact 0
		.amdhsa_exception_int_div_zero 0
	.end_amdhsa_kernel
